# conv deferral (all layer>=1 weights in scan idle CUs) + phase_lr pipelined loads + nt on read-once norm/post loads
# baseline (speedup 1.0000x reference)
; DI void phase_prologue(const Frame& F0, const Args& a) {
;     ...
;         for (int it = gw; it < NITEMS; it += NGW) {
;             int r = it;
;             if (r < 2 * I_IN) { const int j = r / I_IN; r %= I_IN; const int nblk = GIN / 32, kb = r / nblk, nb = r % nblk;
;                 transpose_item(a.gla_w_in + (size_t)j * DM * GIN, DM, GIN, (bf16*)(ws + WS_WIN) + (size_t)j * GIN_PAD * DM, 64 * kb, 32 * nb, 32 * nb, scr, F.lane); continue; }
;             r -= 2 * I_IN;
;             if (r < 2 * I_SQ) { const int j = r / I_SQ; r %= I_SQ; const int kb = r / 64, nb = r % 64;
;                 transpose_item(a.gla_w_out + (size_t)j * DM * DM, DM, DM, (bf16*)(ws + WS_WGO) + (size_t)j * DM * DM, 64 * kb, 32 * nb, 32 * nb, scr, F.lane); continue; }
;             r -= 2 * I_SQ;
;             if (r < 2 * I_SQ) { const int j = r / I_SQ; r %= I_SQ; const int kb = r / 64, nb = r % 64;
;                 transpose_item(a.fnet_w_out + (size_t)j * DM * DM, DM, DM, (bf16*)(ws + WS_WFO) + (size_t)j * DM * DM, 64 * kb, 32 * nb, 32 * nb, scr, F.lane, 1); continue; }
;             r -= 2 * I_SQ;
;             if (r < DEPTH * I_GU) { const int j = r / I_GU; r %= I_GU; const int nblk = 2 * DFF / 32, kb = r / nblk, nb = r % nblk, n0 = 32 * nb;
;                 const int jj = n0 < DFF ? n0 : n0 - DFF; const int drow = (jj >> 7) * 256 + (n0 < DFF ? 0 : 128) + (jj & 127);
;                 transpose_item(a.ffn_w_gu + (size_t)j * DM * 2 * DFF, DM, 2 * DFF, (bf16*)(ws + WS_WGU) + (size_t)j * 2 * DFF * DM, 64 * kb, n0, drow, scr, F.lane); continue; }
;             r -= DEPTH * I_GU;
;             { const int j = r / I_DN; r %= I_DN; const int kb = r / 64, nb = r % 64;
;                 transpose_item(a.ffn_w_down + (size_t)j * DFF * DM, DFF, DM, (bf16*)(ws + WS_WDN) + (size_t)j * DM * DFF, 64 * kb, 32 * nb, 32 * nb, scr, F.lane); }
.LBB0_82:
	s_add_i32 s94, s90, s86
	s_cmp_eq_u32 s92, 0
	s_cbranch_scc1 .Lconv_map0
	s_cmp_eq_u32 s92, 1
	s_cbranch_scc1 .Lconv_map1
	s_cmp_eq_u32 s92, 2
	s_cbranch_scc1 .Lconv_map2
	s_mov_b32 s0, 0xdd30
	s_cmp_lt_i32 s90, 0x4f10
	s_cselect_b32 s0, 0xb130, s0
	s_cmp_lt_i32 s90, 0x800
	s_cselect_b32 s0, 0x4840, s0
	s_add_i32 s6, s90, s0
	s_branch .Lconv_mapped
.Lconv_map2:
	s_mov_b32 s0, 0xb130
	s_cmp_lt_i32 s90, 0x6510
	s_cselect_b32 s0, 0x5420, s0
	s_cmp_lt_i32 s90, 0x2820
	s_cselect_b32 s0, 0x2020, s0
	s_cmp_lt_i32 s90, 0x1820
	s_cselect_b32 s0, 0x1820, s0
	s_add_i32 s6, s90, s0
	s_branch .Lconv_mapped

; DI void phase_prologue(const Frame& F0, const Args& a) {
;     ...
;         const int gw = F.vcu * NWAVES + F.wave, NGW = F.G * NWAVES;
;         constexpr int I_IN = 32 * (GIN / 32), I_SQ = 32 * 64, I_GU = 32 * (2 * DFF / 32), I_DN = (DFF / 64) * 64;
;         constexpr int NITEMS = 2 * I_IN + 2 * I_SQ + 2 * I_SQ + DEPTH * I_GU + DEPTH * I_DN;
;         for (int it = gw; it < NITEMS; it += NGW) {
; DI void phase_scan(const Frame& F0, const Args& a, int colmajor) {
;     ...
;     for (int it = F.vcu; it < 256; it += F.G) {
;         if ((it & 31) >= 16) continue;
.Lconv_scan_idle:
	s_cmp_eq_u32 s3, 0x100
	s_cbranch_scc0 .LBB0_821
	v_writelane_b32 v100, s11, 0
	v_writelane_b32 v100, s20, 1
	v_writelane_b32 v100, s21, 2
	v_writelane_b32 v100, s22, 3
	v_writelane_b32 v100, s26, 4
	v_writelane_b32 v100, s28, 5
	v_writelane_b32 v100, s29, 6
	v_writelane_b32 v100, s30, 7
	v_writelane_b32 v100, s31, 8
	v_writelane_b32 v100, s44, 9
	v_writelane_b32 v100, s45, 10
	v_writelane_b32 v100, s48, 11
	v_writelane_b32 v100, s49, 12
	v_writelane_b32 v100, s50, 13
	v_writelane_b32 v100, s51, 14
	v_writelane_b32 v100, s52, 15
	v_writelane_b32 v100, s53, 16
	v_writelane_b32 v100, s54, 17
	v_writelane_b32 v100, s55, 18
	v_writelane_b32 v100, s57, 19
	v_writelane_b32 v100, s58, 20
	v_writelane_b32 v100, s59, 21
	v_writelane_b32 v100, s64, 22
	v_writelane_b32 v100, s73, 23
	v_writelane_b32 v100, s80, 24
	v_writelane_b32 v100, s81, 25
	v_writelane_b32 v100, s83, 26
	v_writelane_b32 v100, s86, 27
	v_writelane_b32 v100, s87, 28
	v_mov_b32_e32 v101, v1
	v_mov_b32_e32 v102, v3
	v_readlane_b32 s0, v255, 17
	v_readlane_b32 s1, v252, 48
	v_readlane_b32 s44, v252, 49
	v_readlane_b32 s86, v252, 46
	v_readlane_b32 s87, v252, 47
	s_movk_i32 s34, 0xfe00
	s_mov_b32 s65, 0
	s_movk_i32 s70, 0x101
	s_movk_i32 s73, 0x6080
	v_mov_b32_e32 v55, 0
	v_mov_b32_e32 v78, v222
	s_lshr_b32 s4, s1, 5
	s_lshl_b32 s4, s4, 4
	s_and_b32 s5, s1, 15
	s_or_b32 s4, s4, s5
	s_lshl_b32 s4, s4, 3
	s_add_i32 s90, s4, s44
	s_movk_i32 s93, 0x400
	s_mov_b32 s4, 0x7b10
	s_mov_b32 s5, 0x7b10
	s_cmp_eq_u32 s0, 0
	s_cselect_b32 s92, 2, 3
	s_cselect_b32 s91, s4, s5
	s_mov_b32 s6, s90
	s_cmp_lt_i32 s90, s91
	s_cbranch_scc1 .Lconv_entry

; DI f32x4 mfma16(bf16x8 a, bf16x8 b, f32x4 c) { return __builtin_amdgcn_mfma_f32_16x16x32_bf16(a, b, c, 0, 0, 0); }
; DI void phase_lr(const Frame& F0, const Args& a, int jl) {
;     ...
;         for (int ks = 0; ks < 8; ++ks) { const int k = F.wave * 256 + ks * 32 + 8 * l4;
;             const bf16x8 b0 = ld_frag_g(Wl + (size_t)l15 * DM + k), b1 = ld_frag_g(Wl + (size_t)(16 + l15) * DM + k);
; #pragma unroll
;             for (int x = 0; x < 4; ++x) { const bf16x8 af = ld_frag_g(Hb + (size_t)(r0 + x * 16 + l15) * DM + k); acc[x][0] = mfma16(af, b0, acc[x][0]); acc[x][1] = mfma16(af, b1, acc[x][1]); } }
.LBB0_618:
	v_add_u32_e32 v198, s0, v56
	s_add_i32 s1, s1, s3
	v_ashrrev_i32_e32 v199, 31, v198
	v_add_u32_e32 v200, 16, v198
	v_add_u32_e32 v202, 32, v198
	v_add_u32_e32 v204, 48, v198
	v_ashrrev_i32_e32 v201, 31, v200
	v_ashrrev_i32_e32 v203, 31, v202
	v_ashrrev_i32_e32 v205, 31, v204
	v_lshlrev_b64 v[156:157], 12, v[198:199]
	v_lshlrev_b64 v[158:159], 12, v[200:201]
	v_lshlrev_b64 v[160:161], 12, v[202:203]
	v_lshlrev_b64 v[162:163], 12, v[204:205]
	global_load_dwordx4 v[60:63], v[14:15], off
	global_load_dwordx4 v[64:67], v[16:17], off
	v_lshl_add_u64 v[164:165], v[18:19], 0, v[156:157]
	global_load_dwordx4 v[68:71], v[164:165], off
	v_lshl_add_u64 v[164:165], v[18:19], 0, v[158:159]
	global_load_dwordx4 v[72:75], v[164:165], off
	v_lshl_add_u64 v[164:165], v[18:19], 0, v[160:161]
	global_load_dwordx4 v[76:79], v[164:165], off
	v_lshl_add_u64 v[164:165], v[18:19], 0, v[162:163]
	global_load_dwordx4 v[80:83], v[164:165], off
	global_load_dwordx4 v[84:87], v[14:15], off offset:64
	global_load_dwordx4 v[88:91], v[20:21], off
	v_lshl_add_u64 v[164:165], v[22:23], 0, v[156:157]
	global_load_dwordx4 v[92:95], v[164:165], off
	v_lshl_add_u64 v[164:165], v[22:23], 0, v[158:159]
	global_load_dwordx4 v[96:99], v[164:165], off
	v_lshl_add_u64 v[164:165], v[22:23], 0, v[160:161]
	global_load_dwordx4 v[100:103], v[164:165], off
	v_lshl_add_u64 v[164:165], v[22:23], 0, v[162:163]
	global_load_dwordx4 v[104:107], v[164:165], off
	global_load_dwordx4 v[108:111], v[14:15], off offset:128
	global_load_dwordx4 v[112:115], v[24:25], off
	v_lshl_add_u64 v[164:165], v[26:27], 0, v[156:157]
	global_load_dwordx4 v[116:119], v[164:165], off
	v_lshl_add_u64 v[164:165], v[26:27], 0, v[158:159]
	global_load_dwordx4 v[120:123], v[164:165], off
	v_lshl_add_u64 v[164:165], v[26:27], 0, v[160:161]
	global_load_dwordx4 v[124:127], v[164:165], off
	v_lshl_add_u64 v[164:165], v[26:27], 0, v[162:163]
	global_load_dwordx4 v[128:131], v[164:165], off
	global_load_dwordx4 v[132:135], v[14:15], off offset:192
	global_load_dwordx4 v[136:139], v[28:29], off
	v_lshl_add_u64 v[164:165], v[30:31], 0, v[156:157]
	global_load_dwordx4 v[140:143], v[164:165], off
	v_lshl_add_u64 v[164:165], v[30:31], 0, v[158:159]
	global_load_dwordx4 v[144:147], v[164:165], off
	v_lshl_add_u64 v[164:165], v[30:31], 0, v[160:161]
	global_load_dwordx4 v[148:151], v[164:165], off
	v_lshl_add_u64 v[164:165], v[30:31], 0, v[162:163]
	global_load_dwordx4 v[152:155], v[164:165], off
	s_waitcnt vmcnt(18)
	v_mfma_f32_16x16x32_bf16 v[166:169], v[68:71], v[60:63], 0
	v_mfma_f32_16x16x32_bf16 v[170:173], v[68:71], v[64:67], 0
	v_mfma_f32_16x16x32_bf16 v[174:177], v[72:75], v[60:63], 0
	v_mfma_f32_16x16x32_bf16 v[178:181], v[72:75], v[64:67], 0
	v_mfma_f32_16x16x32_bf16 v[182:185], v[76:79], v[60:63], 0
	v_mfma_f32_16x16x32_bf16 v[186:189], v[76:79], v[64:67], 0
	v_mfma_f32_16x16x32_bf16 v[190:193], v[80:83], v[60:63], 0
	v_mfma_f32_16x16x32_bf16 v[194:197], v[80:83], v[64:67], 0
	global_load_dwordx4 v[60:63], v[14:15], off offset:256
	global_load_dwordx4 v[64:67], v[32:33], off
	v_lshl_add_u64 v[164:165], v[34:35], 0, v[156:157]
	global_load_dwordx4 v[68:71], v[164:165], off
	v_lshl_add_u64 v[164:165], v[34:35], 0, v[158:159]
	global_load_dwordx4 v[72:75], v[164:165], off
	v_lshl_add_u64 v[164:165], v[34:35], 0, v[160:161]
	global_load_dwordx4 v[76:79], v[164:165], off
	v_lshl_add_u64 v[164:165], v[34:35], 0, v[162:163]
	global_load_dwordx4 v[80:83], v[164:165], off
	s_waitcnt vmcnt(18)
	v_mfma_f32_16x16x32_bf16 v[166:169], v[92:95], v[84:87], v[166:169]
	v_mfma_f32_16x16x32_bf16 v[170:173], v[92:95], v[88:91], v[170:173]
	v_mfma_f32_16x16x32_bf16 v[174:177], v[96:99], v[84:87], v[174:177]
	v_mfma_f32_16x16x32_bf16 v[178:181], v[96:99], v[88:91], v[178:181]
	v_mfma_f32_16x16x32_bf16 v[182:185], v[100:103], v[84:87], v[182:185]
	v_mfma_f32_16x16x32_bf16 v[186:189], v[100:103], v[88:91], v[186:189]
	v_mfma_f32_16x16x32_bf16 v[190:193], v[104:107], v[84:87], v[190:193]
	v_mfma_f32_16x16x32_bf16 v[194:197], v[104:107], v[88:91], v[194:197]
	global_load_dwordx4 v[84:87], v[14:15], off offset:320
	global_load_dwordx4 v[88:91], v[36:37], off
	v_lshl_add_u64 v[164:165], v[38:39], 0, v[156:157]
	global_load_dwordx4 v[92:95], v[164:165], off
	v_lshl_add_u64 v[164:165], v[38:39], 0, v[158:159]
	global_load_dwordx4 v[96:99], v[164:165], off
	v_lshl_add_u64 v[164:165], v[38:39], 0, v[160:161]
	global_load_dwordx4 v[100:103], v[164:165], off
	v_lshl_add_u64 v[164:165], v[38:39], 0, v[162:163]
	global_load_dwordx4 v[104:107], v[164:165], off
	s_waitcnt vmcnt(18)
	v_mfma_f32_16x16x32_bf16 v[166:169], v[116:119], v[108:111], v[166:169]
	v_mfma_f32_16x16x32_bf16 v[170:173], v[116:119], v[112:115], v[170:173]
	v_mfma_f32_16x16x32_bf16 v[174:177], v[120:123], v[108:111], v[174:177]
	v_mfma_f32_16x16x32_bf16 v[178:181], v[120:123], v[112:115], v[178:181]
	v_mfma_f32_16x16x32_bf16 v[182:185], v[124:127], v[108:111], v[182:185]
	v_mfma_f32_16x16x32_bf16 v[186:189], v[124:127], v[112:115], v[186:189]
	v_mfma_f32_16x16x32_bf16 v[190:193], v[128:131], v[108:111], v[190:193]
	v_mfma_f32_16x16x32_bf16 v[194:197], v[128:131], v[112:115], v[194:197]
	global_load_dwordx4 v[108:111], v[14:15], off offset:384
	global_load_dwordx4 v[112:115], v[40:41], off
	v_lshl_add_u64 v[164:165], v[42:43], 0, v[156:157]
	global_load_dwordx4 v[116:119], v[164:165], off
	v_lshl_add_u64 v[164:165], v[42:43], 0, v[158:159]
	global_load_dwordx4 v[120:123], v[164:165], off
	v_lshl_add_u64 v[164:165], v[42:43], 0, v[160:161]
	global_load_dwordx4 v[124:127], v[164:165], off
	v_lshl_add_u64 v[164:165], v[42:43], 0, v[162:163]
	global_load_dwordx4 v[128:131], v[164:165], off
	s_waitcnt vmcnt(18)
; DI f32x4 mfma16(bf16x8 a, bf16x8 b, f32x4 c) { return __builtin_amdgcn_mfma_f32_16x16x32_bf16(a, b, c, 0, 0, 0); }
; DI void phase_lr(const Frame& F0, const Args& a, int jl) {
;     ...
;         for (int ks = 0; ks < 8; ++ks) { const int k = F.wave * 256 + ks * 32 + 8 * l4;
;             const bf16x8 b0 = ld_frag_g(Wl + (size_t)l15 * DM + k), b1 = ld_frag_g(Wl + (size_t)(16 + l15) * DM + k);
; #pragma unroll
;             for (int x = 0; x < 4; ++x) { const bf16x8 af = ld_frag_g(Hb + (size_t)(r0 + x * 16 + l15) * DM + k); acc[x][0] = mfma16(af, b0, acc[x][0]); acc[x][1] = mfma16(af, b1, acc[x][1]); } }
; #pragma unroll
;         for (int x = 0; x < 4; ++x)
; #pragma unroll
;             for (int y = 0; y < 2; ++y) red[(F.wave * 8 + x * 2 + y) * 64 + F.lane] = acc[x][y];
;         __syncthreads();
;         { const int t = F.wave; f32x4 s = red[t * 64 + F.lane];
; #pragma unroll
;             for (int w = 1; w < 8; ++w) s += red[(w * 8 + t) * 64 + F.lane];
;             const int x = t >> 1, y = t & 1;
; #pragma unroll
;             for (int r = 0; r < 4; ++r) LR[(size_t)(r0 + x * 16 + 4 * l4 + r) * 32 + y * 16 + l15] = s[r]; }
;         __syncthreads();
	v_mfma_f32_16x16x32_bf16 v[166:169], v[140:143], v[132:135], v[166:169]
	v_mfma_f32_16x16x32_bf16 v[170:173], v[140:143], v[136:139], v[170:173]
	v_mfma_f32_16x16x32_bf16 v[174:177], v[144:147], v[132:135], v[174:177]
	v_mfma_f32_16x16x32_bf16 v[178:181], v[144:147], v[136:139], v[178:181]
	v_mfma_f32_16x16x32_bf16 v[182:185], v[148:151], v[132:135], v[182:185]
	v_mfma_f32_16x16x32_bf16 v[186:189], v[148:151], v[136:139], v[186:189]
	v_mfma_f32_16x16x32_bf16 v[190:193], v[152:155], v[132:135], v[190:193]
	v_mfma_f32_16x16x32_bf16 v[194:197], v[152:155], v[136:139], v[194:197]
	global_load_dwordx4 v[132:135], v[14:15], off offset:448
	global_load_dwordx4 v[136:139], v[44:45], off
	v_lshl_add_u64 v[164:165], v[46:47], 0, v[156:157]
	global_load_dwordx4 v[140:143], v[164:165], off
	v_lshl_add_u64 v[164:165], v[46:47], 0, v[158:159]
	global_load_dwordx4 v[144:147], v[164:165], off
	v_lshl_add_u64 v[164:165], v[46:47], 0, v[160:161]
	global_load_dwordx4 v[148:151], v[164:165], off
	v_lshl_add_u64 v[164:165], v[46:47], 0, v[162:163]
	global_load_dwordx4 v[152:155], v[164:165], off
	s_waitcnt vmcnt(18)
	v_mfma_f32_16x16x32_bf16 v[166:169], v[68:71], v[60:63], v[166:169]
	v_mfma_f32_16x16x32_bf16 v[170:173], v[68:71], v[64:67], v[170:173]
	v_mfma_f32_16x16x32_bf16 v[174:177], v[72:75], v[60:63], v[174:177]
	v_mfma_f32_16x16x32_bf16 v[178:181], v[72:75], v[64:67], v[178:181]
	v_mfma_f32_16x16x32_bf16 v[182:185], v[76:79], v[60:63], v[182:185]
	v_mfma_f32_16x16x32_bf16 v[186:189], v[76:79], v[64:67], v[186:189]
	v_mfma_f32_16x16x32_bf16 v[190:193], v[80:83], v[60:63], v[190:193]
	v_mfma_f32_16x16x32_bf16 v[194:197], v[80:83], v[64:67], v[194:197]
	s_waitcnt vmcnt(12)
	v_mfma_f32_16x16x32_bf16 v[166:169], v[92:95], v[84:87], v[166:169]
	v_mfma_f32_16x16x32_bf16 v[170:173], v[92:95], v[88:91], v[170:173]
	v_mfma_f32_16x16x32_bf16 v[174:177], v[96:99], v[84:87], v[174:177]
	v_mfma_f32_16x16x32_bf16 v[178:181], v[96:99], v[88:91], v[178:181]
	v_mfma_f32_16x16x32_bf16 v[182:185], v[100:103], v[84:87], v[182:185]
	v_mfma_f32_16x16x32_bf16 v[186:189], v[100:103], v[88:91], v[186:189]
	v_mfma_f32_16x16x32_bf16 v[190:193], v[104:107], v[84:87], v[190:193]
	v_mfma_f32_16x16x32_bf16 v[194:197], v[104:107], v[88:91], v[194:197]
	s_waitcnt vmcnt(6)
	v_mfma_f32_16x16x32_bf16 v[166:169], v[116:119], v[108:111], v[166:169]
	v_mfma_f32_16x16x32_bf16 v[170:173], v[116:119], v[112:115], v[170:173]
	v_mfma_f32_16x16x32_bf16 v[174:177], v[120:123], v[108:111], v[174:177]
	v_mfma_f32_16x16x32_bf16 v[178:181], v[120:123], v[112:115], v[178:181]
	v_mfma_f32_16x16x32_bf16 v[182:185], v[124:127], v[108:111], v[182:185]
	v_mfma_f32_16x16x32_bf16 v[186:189], v[124:127], v[112:115], v[186:189]
	v_mfma_f32_16x16x32_bf16 v[190:193], v[128:131], v[108:111], v[190:193]
	v_mfma_f32_16x16x32_bf16 v[194:197], v[128:131], v[112:115], v[194:197]
	s_waitcnt vmcnt(0)
	v_mfma_f32_16x16x32_bf16 v[166:169], v[140:143], v[132:135], v[166:169]
	v_mfma_f32_16x16x32_bf16 v[170:173], v[140:143], v[136:139], v[170:173]
	v_mfma_f32_16x16x32_bf16 v[174:177], v[144:147], v[132:135], v[174:177]
	v_mfma_f32_16x16x32_bf16 v[178:181], v[144:147], v[136:139], v[178:181]
	v_mfma_f32_16x16x32_bf16 v[182:185], v[148:151], v[132:135], v[182:185]
	v_mfma_f32_16x16x32_bf16 v[186:189], v[148:151], v[136:139], v[186:189]
	v_mfma_f32_16x16x32_bf16 v[190:193], v[152:155], v[132:135], v[190:193]
	v_mfma_f32_16x16x32_bf16 v[194:197], v[152:155], v[136:139], v[194:197]
	s_nop 7
	ds_write_b128 v57, v[166:169]
	ds_write_b128 v57, v[170:173] offset:1024
	ds_write_b128 v57, v[174:177] offset:2048
	ds_write_b128 v57, v[178:181] offset:3072
	ds_write_b128 v57, v[182:185] offset:4096
	ds_write_b128 v57, v[186:189] offset:5120
	ds_write_b128 v57, v[190:193] offset:6144
	ds_write_b128 v57, v[194:197] offset:7168
	s_waitcnt lgkmcnt(0)
	s_barrier
	ds_read_b128 v[4:7], v58
	ds_read_b128 v[8:11], v58 offset:8192
	s_waitcnt lgkmcnt(0)
	v_pk_add_f32 v[10:11], v[6:7], v[10:11]
	v_pk_add_f32 v[8:9], v[4:5], v[8:9]
	ds_read_b128 v[4:7], v58 offset:16384
	s_waitcnt lgkmcnt(0)
	v_pk_add_f32 v[10:11], v[10:11], v[6:7]
	v_pk_add_f32 v[8:9], v[8:9], v[4:5]
	ds_read_b128 v[4:7], v58 offset:24576
	s_waitcnt lgkmcnt(0)
	v_pk_add_f32 v[10:11], v[10:11], v[6:7]
	v_pk_add_f32 v[8:9], v[8:9], v[4:5]
	ds_read_b128 v[4:7], v58 offset:32768
	s_waitcnt lgkmcnt(0)
	v_pk_add_f32 v[10:11], v[10:11], v[6:7]
	v_pk_add_f32 v[8:9], v[8:9], v[4:5]
	ds_read_b128 v[4:7], v58 offset:40960
	s_waitcnt lgkmcnt(0)
	v_pk_add_f32 v[10:11], v[10:11], v[6:7]
	v_pk_add_f32 v[8:9], v[8:9], v[4:5]
	ds_read_b128 v[4:7], v58 offset:49152
	s_waitcnt lgkmcnt(0)
	v_pk_add_f32 v[10:11], v[10:11], v[6:7]
	v_pk_add_f32 v[8:9], v[8:9], v[4:5]
	ds_read_b128 v[4:7], v58 offset:57344
	s_waitcnt lgkmcnt(0)
	v_pk_add_f32 v[4:5], v[8:9], v[4:5]
	v_add_u32_e32 v8, s0, v2
	v_ashrrev_i32_e32 v9, 31, v8
	v_pk_add_f32 v[6:7], v[10:11], v[6:7]
	v_lshlrev_b64 v[10:11], 7, v[8:9]
	v_lshl_add_u64 v[10:11], v[12:13], 0, v[10:11]
	flat_store_dword v[10:11], v4
	v_add_u32_e32 v10, 1, v8
	v_ashrrev_i32_e32 v11, 31, v10
	v_lshlrev_b64 v[10:11], 7, v[10:11]
	v_lshl_add_u64 v[10:11], v[12:13], 0, v[10:11]
	v_add_u32_e32 v4, 2, v8
	flat_store_dword v[10:11], v5
	v_ashrrev_i32_e32 v5, 31, v4
	v_lshlrev_b64 v[4:5], 7, v[4:5]
	v_lshl_add_u64 v[4:5], v[12:13], 0, v[4:5]
	flat_store_dword v[4:5], v6
	v_add_u32_e32 v4, 3, v8
	v_ashrrev_i32_e32 v5, 31, v4
	v_lshlrev_b64 v[4:5], 7, v[4:5]
	s_add_i32 s0, s0, s4
	v_lshl_add_u64 v[4:5], v[12:13], 0, v[4:5]
	s_cmpk_lt_i32 s1, 0x88
	flat_store_dword v[4:5], v7
	s_waitcnt lgkmcnt(0)
	s_barrier
	s_cbranch_scc1 .LBB0_618
	s_branch .LBB0_565

; #define GAS __attribute__((address_space(1)))
; DI float wave_sum(float v) {
; #pragma unroll
;     for (int o = 1; o < 64; o <<= 1) v += __shfl_xor(v, o);
;     return v;
; DI void phase_gla_post(const Frame& F0, const Args& a, int jl, int nrows) {
;     ...
;     const f32x4 g0 = *(const GAS f32x4*)(a.gla_head_gain + (size_t)jl * HV + F.lane * 8), g1 = *(const GAS f32x4*)(a.gla_head_gain + (size_t)jl * HV + F.lane * 8 + 4);
;     v4u of[4], ob[4], rr[4];
;     const int nfull = nrows / NGW, xr = F.wave * F.G + F.vcu, nit = nfull + (xr < nrows - nfull * NGW ? 1 : 0);
;     ...
;     if (nit > 0) { const int R0 = POST_ROW(0);
; #pragma unroll
;         for (int j = 0; j < 4; ++j) { const size_t off = (size_t)R0 * VD + j * HV + F.lane * 8;
;             of[j] = *(const GAS v4u*)(O + off); ob[j] = *(const GAS v4u*)(O + (size_t)MROWS * VD + off); rr[j] = *(const GAS v4u*)(Rb + off); } }
.LBB0_906:
	s_mov_b32 s13, s52
	v_mov_b32_e32 v2, v222
	s_mov_b32 s14, s51
	s_waitcnt vmcnt(0)
	v_mov_b32_e32 v4, v0
	s_mul_i32 s12, s13, s3
	s_add_i32 s12, s12, s14
	s_cmp_lt_i32 s12, s8
	s_cselect_b64 s[16:17], -1, 0
	s_cmp_lg_u64 s[16:17], 0
	s_addc_u32 s10, s6, 0
	s_mov_b64 s[4:5], s[30:31]
	s_cmp_lt_i32 s10, 1
	s_cbranch_scc1 .LBB0_905
	s_add_u32 s40, s4, 0x29a84000
	s_addc_u32 s41, s5, 0
	s_add_u32 s42, s4, 0x207e4000
	s_addc_u32 s43, s5, 0
	s_lshl_b32 s14, s14, 3
	s_add_i32 s15, s14, s13
	s_add_i32 s12, s7, s12
	s_and_b64 s[16:17], s[38:39], exec
	s_cselect_b32 s16, s15, s12
	v_lshlrev_b32_e32 v108, 3, v2
	s_ashr_i32 s17, s16, 31
	v_ashrrev_i32_e32 v109, 31, v108
	s_lshl_b64 s[16:17], s[16:17], 11
	v_lshl_add_u64 v[12:13], s[16:17], 0, v[108:109]
	s_add_u32 s44, s4, 0x2bc84000
	v_lshlrev_b64 v[12:13], 1, v[12:13]
	v_lshl_add_u64 v[8:9], v[108:109], 2, s[0:1]
	s_addc_u32 s45, s5, 0
	v_lshl_add_u64 v[14:15], s[40:41], 0, v[12:13]
	global_load_dwordx4 v[4:7], v[8:9], off nt
	s_nop 0
	global_load_dwordx4 v[8:11], v[8:9], off offset:16 nt
	v_lshl_add_u64 v[16:17], s[44:45], 0, v[12:13]
	v_lshl_add_u64 v[12:13], s[42:43], 0, v[12:13]
	global_load_dwordx4 v[104:107], v[14:15], off nt
	global_load_dwordx4 v[96:99], v[14:15], off offset:1024 nt
	global_load_dwordx4 v[100:103], v[16:17], off nt
	global_load_dwordx4 v[92:95], v[16:17], off offset:1024 nt
	global_load_dwordx4 v[84:87], v[12:13], off nt
	global_load_dwordx4 v[88:91], v[12:13], off offset:1024 nt
	global_load_dwordx4 v[80:83], v[14:15], off offset:2048 nt
	global_load_dwordx4 v[68:71], v[14:15], off offset:3072 nt
	global_load_dwordx4 v[76:79], v[16:17], off offset:2048 nt
	global_load_dwordx4 v[64:67], v[16:17], off offset:3072 nt
	global_load_dwordx4 v[72:75], v[12:13], off offset:2048 nt
	global_load_dwordx4 v[24:27], v[12:13], off offset:3072 nt
	v_lshl_add_u64 v[12:13], v[108:109], 1, s[4:5]
	s_mov_b64 s[4:5], 0x1a1e4000
	v_and_b32_e32 v2, 64, v224
	v_lshl_add_u64 v[110:111], v[12:13], 0, s[4:5]
	v_add_u32_e32 v12, 64, v2
	v_xor_b32_e32 v2, 1, v224
	v_cmp_lt_i32_e32 vcc, v2, v12
	v_xor_b32_e32 v13, 2, v224
	s_mov_b32 s16, 0
	v_cndmask_b32_e32 v2, v224, v2, vcc
	v_cmp_lt_i32_e32 vcc, v13, v12
	v_lshlrev_b32_e32 v2, 2, v2
	s_nop 0
	v_cndmask_b32_e32 v13, v224, v13, vcc
	v_lshlrev_b32_e32 v112, 2, v13
	v_xor_b32_e32 v13, 4, v224
	v_cmp_lt_i32_e32 vcc, v13, v12
	s_nop 1
	v_cndmask_b32_e32 v13, v224, v13, vcc
	v_lshlrev_b32_e32 v113, 2, v13
	v_xor_b32_e32 v13, 8, v224
	v_cmp_lt_i32_e32 vcc, v13, v12
	s_nop 1
	v_cndmask_b32_e32 v13, v224, v13, vcc
	v_lshlrev_b32_e32 v114, 2, v13
	v_xor_b32_e32 v13, 16, v224
	v_cmp_lt_i32_e32 vcc, v13, v12
	s_nop 1
	v_cndmask_b32_e32 v13, v224, v13, vcc
	v_lshlrev_b32_e32 v115, 2, v13
	v_xor_b32_e32 v13, 32, v224
	v_cmp_lt_i32_e32 vcc, v13, v12
	s_nop 1
	v_cndmask_b32_e32 v12, v224, v13, vcc
	v_lshlrev_b32_e32 v116, 2, v12
	s_branch .LBB0_909

; #define GAS __attribute__((address_space(1)))
; DI void phase_gla_post(const Frame& F0, const Args& a, int jl, int nrows) {
;     ...
;         v4u ofn[4], obn[4], rrn[4]; const int Rn = POST_ROW(it + 1);
;         if (it + 1 < nit) {
; #pragma unroll
;             for (int j = 0; j < 4; ++j) { const size_t off = (size_t)Rn * VD + j * HV + F.lane * 8;
;                 ofn[j] = *(const GAS v4u*)(O + off); obn[j] = *(const GAS v4u*)(O + (size_t)MROWS * VD + off); rrn[j] = *(const GAS v4u*)(Rb + off); } }
.LBB0_911:
	s_andn2_b64 vcc, exec, s[4:5]
	s_cbranch_vccnz .LBB0_908
	s_add_i32 s14, s57, s15
	s_cmp_lt_i32 s13, s6
	s_cselect_b32 s4, s14, s12
	s_ashr_i32 s5, s4, 31
	s_lshl_b64 s[4:5], s[4:5], 11
	v_lshl_add_u64 v[12:13], s[4:5], 0, v[108:109]
	v_lshlrev_b64 v[12:13], 1, v[12:13]
	v_lshl_add_u64 v[28:29], s[40:41], 0, v[12:13]
	v_lshl_add_u64 v[40:41], s[44:45], 0, v[12:13]
	v_lshl_add_u64 v[56:57], s[42:43], 0, v[12:13]
	global_load_dwordx4 v[12:15], v[28:29], off nt
	global_load_dwordx4 v[16:19], v[28:29], off offset:1024 nt
	global_load_dwordx4 v[36:39], v[40:41], off nt
	global_load_dwordx4 v[32:35], v[40:41], off offset:1024 nt
	global_load_dwordx4 v[52:55], v[56:57], off nt
	global_load_dwordx4 v[48:51], v[56:57], off offset:1024 nt
	global_load_dwordx4 v[20:23], v[28:29], off offset:2048 nt
	s_nop 0
	global_load_dwordx4 v[28:31], v[28:29], off offset:3072 nt
	s_nop 0
	global_load_dwordx4 v[44:47], v[40:41], off offset:2048 nt
	s_nop 0
	global_load_dwordx4 v[40:43], v[40:41], off offset:3072 nt
	s_nop 0
	global_load_dwordx4 v[60:63], v[56:57], off offset:2048 nt
	s_nop 0
	global_load_dwordx4 v[56:59], v[56:57], off offset:3072 nt
	s_branch .LBB0_908

; #define GAS __attribute__((address_space(1)))
; DI void norm_load_x(f32x4 (&v)[8], const void* xlat, const void* xctx, int xin_bf16, int R, int co) {
;     if (xin_bf16) { const bf16* xr = R < NLAT ? (const bf16*)xlat + (size_t)R * DM : (const bf16*)xctx + (size_t)(R - NLAT) * DM;
;         v2u t[8];
; #pragma unroll
;         for (int j = 0; j < 8; ++j) t[j] = *(const GAS v2u*)(xr + j * 256 + co);
; #pragma unroll
;         for (int j = 0; j < 8; ++j) v[j] = (f32x4){bflo(t[j].x), bfhi(t[j].x), bflo(t[j].y), bfhi(t[j].y)}; }
; DI void phase_norm(const Frame& F0, int nrows, const void* xlat, const void* xctx, int xin_bf16, const bf16* Y, const float* gainY, const float* gate  ,
;                    void* Xout_lat, void* Xout_ctx, int xout_bf16, bf16* Hout, const float* gainH, const float* shift, const float* scale) {
;     ...
;     if (nit > 0) { const int R0 = NORM_ROW(0); norm_load_x(v, xlat, xctx, xin_bf16, R0, co);
.LBB0_1073:
	s_add_i32 s10, s34, 0xffffe000
	s_ashr_i32 s35, s34, 31
	v_lshlrev_b32_e32 v164, 2, v2
	s_cmpk_lt_i32 s34, 0x2000
	s_cselect_b32 s47, s35, 0
	s_cselect_b32 s46, s34, s10
	s_cselect_b32 s10, s37, s59
	s_cselect_b32 s18, s36, s58
	s_and_b64 vcc, exec, s[88:89]
	v_ashrrev_i32_e32 v165, 31, v164
	s_cbranch_vccnz .LBB0_1092
	s_lshl_b64 s[20:21], s[46:47], 12
	s_add_u32 s20, s18, s20
	s_addc_u32 s21, s10, s21
	v_lshl_add_u64 v[4:5], v[164:165], 1, s[20:21]
	global_load_dwordx2 v[6:7], v[4:5], off nt
	global_load_dwordx2 v[8:9], v[4:5], off offset:512 nt
	global_load_dwordx2 v[10:11], v[4:5], off offset:1024 nt
	global_load_dwordx2 v[12:13], v[4:5], off offset:1536 nt
	global_load_dwordx2 v[14:15], v[4:5], off offset:2048 nt
	global_load_dwordx2 v[16:17], v[4:5], off offset:2560 nt
	global_load_dwordx2 v[18:19], v[4:5], off offset:3072 nt
	s_nop 0
	global_load_dwordx2 v[4:5], v[4:5], off offset:3584 nt
	s_waitcnt vmcnt(7)
	v_lshlrev_b32_e32 v120, 16, v6
	v_and_b32_e32 v121, 0xffff0000, v6
	v_lshlrev_b32_e32 v122, 16, v7
	v_and_b32_e32 v123, 0xffff0000, v7
	s_waitcnt vmcnt(6)
	v_lshlrev_b32_e32 v116, 16, v8
	v_and_b32_e32 v117, 0xffff0000, v8
	v_lshlrev_b32_e32 v118, 16, v9
	v_and_b32_e32 v119, 0xffff0000, v9
	s_waitcnt vmcnt(5)
	v_lshlrev_b32_e32 v128, 16, v10
	v_and_b32_e32 v129, 0xffff0000, v10
	v_lshlrev_b32_e32 v130, 16, v11
	v_and_b32_e32 v131, 0xffff0000, v11
	s_waitcnt vmcnt(4)
	v_lshlrev_b32_e32 v124, 16, v12
	v_and_b32_e32 v125, 0xffff0000, v12
	v_lshlrev_b32_e32 v126, 16, v13
	v_and_b32_e32 v127, 0xffff0000, v13
	s_waitcnt vmcnt(3)
	v_lshlrev_b32_e32 v136, 16, v14
	v_and_b32_e32 v137, 0xffff0000, v14
	v_lshlrev_b32_e32 v138, 16, v15
	v_and_b32_e32 v139, 0xffff0000, v15
	s_waitcnt vmcnt(2)
	v_lshlrev_b32_e32 v132, 16, v16
	v_and_b32_e32 v133, 0xffff0000, v16
	v_lshlrev_b32_e32 v134, 16, v17
	v_and_b32_e32 v135, 0xffff0000, v17
	s_waitcnt vmcnt(1)
	v_lshlrev_b32_e32 v148, 16, v18
	v_and_b32_e32 v149, 0xffff0000, v18
	v_lshlrev_b32_e32 v150, 16, v19
	v_and_b32_e32 v151, 0xffff0000, v19
	s_waitcnt vmcnt(0)
	v_lshlrev_b32_e32 v140, 16, v4
	v_and_b32_e32 v141, 0xffff0000, v4
	v_lshlrev_b32_e32 v142, 16, v5
	v_and_b32_e32 v143, 0xffff0000, v5
	s_cbranch_execnz .LBB0_1076

; #define GAS __attribute__((address_space(1)))
; DI void phase_norm(const Frame& F0, int nrows, const void* xlat, const void* xctx, int xin_bf16, const bf16* Y, const float* gainY, const float* gate  ,
;                    void* Xout_lat, void* Xout_ctx, int xout_bf16, bf16* Hout, const float* gainH, const float* shift, const float* scale) {
;     ...
;     if (nit > 0) { const int R0 = NORM_ROW(0); norm_load_x(v, xlat, xctx, xin_bf16, R0, co);
;         if (Y) {
; #pragma unroll
;             for (int j = 0; j < 8; ++j) yb[j] = *(const GAS v2u*)(Y + (size_t)R0 * DM + j * 256 + co); } }
;     f32x4 gt[8], sh[8], sc[8]; int mbp = -1;
;     for (int it = 0; it < nit; ++it) {
;         const int R = NORM_ROW(it); const int mb = row_mb(R), Rn = NORM_ROW(it + 1);
;         f32x4 vn[8]; v2u ybn[8];
;         if (it + 1 < nit) { norm_load_x(vn, xlat, xctx, xin_bf16, Rn, co);
;             if (Y) {
; #pragma unroll
;                 for (int j = 0; j < 8; ++j) ybn[j] = *(const GAS v2u*)(Y + (size_t)Rn * DM + j * 256 + co); } }
;         if (mb != mbp) { mbp = mb;
;             if (Y) {
; #pragma unroll
;                 for (int j = 0; j < 8; ++j) gt[j] = *(const GAS f32x4*)(gate + (size_t)mb * NADA + j * 256 + co); }
;             if (Hout) {
; #pragma unroll
;                 for (int j = 0; j < 8; ++j) { sh[j] = *(const GAS f32x4*)(shift + (size_t)mb * NADA + j * 256 + co); sc[j] = *(const GAS f32x4*)(scale + (size_t)mb * NADA + j * 256 + co); } } }
.LBB0_1076:
	s_add_u32 s8, s8, 0x2de84000
	s_addc_u32 s9, s9, 0
	s_add_u32 s18, s4, 0x15de4000
	s_addc_u32 s19, s5, 0
	s_add_u32 s20, s6, 0x17de4000
	s_addc_u32 s21, s7, 0
	s_lshl_b64 s[4:5], s[34:35], 12
	s_add_u32 s4, s8, s4
	s_addc_u32 s5, s9, s5
	v_lshlrev_b64 v[4:5], 1, v[164:165]
	v_lshl_add_u64 v[6:7], s[4:5], 0, v[4:5]
	global_load_dwordx2 v[192:193], v[6:7], off offset:3584 nt
	global_load_dwordx2 v[194:195], v[6:7], off offset:3072 nt
	global_load_dwordx2 v[196:197], v[6:7], off offset:2560 nt
	global_load_dwordx2 v[198:199], v[6:7], off offset:2048 nt
	global_load_dwordx2 v[200:201], v[6:7], off offset:1536 nt
	global_load_dwordx2 v[202:203], v[6:7], off offset:1024 nt
	global_load_dwordx2 v[204:205], v[6:7], off offset:512 nt
	global_load_dwordx2 v[206:207], v[6:7], off nt
	v_lshl_add_u64 v[166:167], s[8:9], 0, v[4:5]
	v_lshl_add_u64 v[4:5], s[0:1], 0, v[4:5]
	s_mov_b64 s[0:1], 0x1a1e4000
	v_and_b32_e32 v2, 64, v224
	v_lshl_add_u64 v[174:175], v[4:5], 0, s[0:1]
	v_add_u32_e32 v4, 64, v2
	v_xor_b32_e32 v2, 1, v224
	v_cmp_lt_i32_e32 vcc, v2, v4
	v_xor_b32_e32 v5, 2, v224
	s_ashr_i32 s0, s17, 31
	v_readlane_b32 s1, v254, 48
	v_cndmask_b32_e32 v2, v224, v2, vcc
	v_cmp_lt_i32_e32 vcc, v5, v4
	s_xor_b32 s0, s0, s1
	s_abs_i32 s1, s17
	v_readlane_b32 s5, v254, 28
	v_cndmask_b32_e32 v5, v224, v5, vcc
	s_mul_hi_u32 s5, s1, s5
	v_readlane_b32 s8, v254, 27
	v_lshlrev_b32_e32 v208, 2, v5
	v_xor_b32_e32 v5, 4, v224
	s_mul_i32 s6, s5, s8
	v_cmp_lt_i32_e32 vcc, v5, v4
	s_sub_i32 s1, s1, s6
	s_add_i32 s24, s24, s13
	s_and_b32 s4, s17, 0x3ff
	v_cndmask_b32_e32 v5, v224, v5, vcc
	s_add_i32 s6, s5, 1
	s_sub_i32 s7, s1, s8
	v_lshlrev_b32_e32 v209, 2, v5
	v_xor_b32_e32 v5, 8, v224
	s_cmp_ge_u32 s1, s8
	v_cmp_lt_i32_e32 vcc, v5, v4
	s_cselect_b32 s5, s6, s5
	s_cselect_b32 s1, s7, s1
	v_cndmask_b32_e32 v5, v224, v5, vcc
	s_add_i32 s6, s5, 1
	v_lshlrev_b32_e32 v210, 2, v5
	v_xor_b32_e32 v5, 16, v224
	s_cmp_ge_u32 s1, s8
	v_cmp_lt_i32_e32 vcc, v5, v4
	s_cselect_b32 s1, s6, s5
	s_xor_b32 s1, s1, s0
	v_cndmask_b32_e32 v5, v224, v5, vcc
	v_lshlrev_b32_e32 v211, 2, v5
	v_xor_b32_e32 v5, 32, v224
	s_lshl_b32 s1, s1, 12
	v_cmp_lt_i32_e32 vcc, v5, v4
	s_or_b32 s1, s1, s4
	s_lshl_b32 s0, s0, 12
	v_lshlrev_b64 v[6:7], 2, v[164:165]
	v_cndmask_b32_e32 v4, v224, v5, vcc
	s_sub_i32 s28, s1, s0
	s_bitset1_b32 s1, 10
	v_mov_b32_e32 v84, 0
	v_lshl_add_u64 v[168:169], s[38:39], 0, v[6:7]
	v_lshl_add_u64 v[170:171], s[40:41], 0, v[6:7]
	v_lshl_add_u64 v[172:173], s[42:43], 0, v[6:7]
	s_mov_b32 s25, 0
	s_mov_b32 s10, -1
	v_lshlrev_b32_e32 v2, 2, v2
	v_lshlrev_b32_e32 v212, 2, v4
	s_sub_i32 s29, s1, s0
	v_mov_b32_e32 v85, v84
	v_mov_b32_e32 v86, v84
	v_mov_b32_e32 v87, v84
	v_mov_b32_e32 v104, v84
	v_mov_b32_e32 v105, v84
	v_mov_b32_e32 v106, v84
	v_mov_b32_e32 v107, v84
	v_mov_b32_e32 v108, v84
	v_mov_b32_e32 v109, v84
	v_mov_b32_e32 v110, v84
	v_mov_b32_e32 v111, v84
	v_mov_b32_e32 v112, v84
	v_mov_b32_e32 v113, v84
	v_mov_b32_e32 v114, v84
	v_mov_b32_e32 v115, v84
	v_mov_b32_e32 v144, v84
	v_mov_b32_e32 v145, v84
	v_mov_b32_e32 v146, v84
	v_mov_b32_e32 v147, v84
	v_mov_b32_e32 v152, v84
	v_mov_b32_e32 v153, v84
	v_mov_b32_e32 v154, v84
	v_mov_b32_e32 v155, v84
	v_mov_b32_e32 v156, v84
	v_mov_b32_e32 v157, v84
	v_mov_b32_e32 v158, v84
	v_mov_b32_e32 v159, v84
	v_mov_b32_e32 v160, v84
	v_mov_b32_e32 v161, v84
	s_waitcnt lgkmcnt(0)
	v_mov_b32_e32 v162, v84
	v_mov_b32_e32 v163, v84
	s_branch .LBB0_1078

; #define GAS __attribute__((address_space(1)))
; DI void norm_load_x(f32x4 (&v)[8], const void* xlat, const void* xctx, int xin_bf16, int R, int co) {
;     if (xin_bf16) { const bf16* xr = R < NLAT ? (const bf16*)xlat + (size_t)R * DM : (const bf16*)xctx + (size_t)(R - NLAT) * DM;
;         v2u t[8];
; #pragma unroll
;         for (int j = 0; j < 8; ++j) t[j] = *(const GAS v2u*)(xr + j * 256 + co);
; #pragma unroll
;         for (int j = 0; j < 8; ++j) v[j] = (f32x4){bflo(t[j].x), bfhi(t[j].x), bflo(t[j].y), bfhi(t[j].y)}; }
; DI void phase_norm(const Frame& F0, int nrows, const void* xlat, const void* xctx, int xin_bf16, const bf16* Y, const float* gainY, const float* gate  ,
;                    void* Xout_lat, void* Xout_ctx, int xout_bf16, bf16* Hout, const float* gainH, const float* shift, const float* scale) {
;     ...
;         const int R = NORM_ROW(it); const int mb = row_mb(R), Rn = NORM_ROW(it + 1);
;         f32x4 vn[8]; v2u ybn[8];
;         if (it + 1 < nit) { norm_load_x(vn, xlat, xctx, xin_bf16, Rn, co);
.LBB0_1084:
	s_cmp_ge_i32 s25, s16
	s_cbranch_scc1 .LBB0_1089
	s_add_i32 s1, s4, 0xffffe000
	s_ashr_i32 s5, s4, 31
	s_cmpk_lt_i32 s4, 0x2000
	s_cselect_b32 s7, s5, 0
	s_cselect_b32 s6, s4, s1
	s_cselect_b32 s1, s37, s59
	s_cselect_b32 s22, s36, s58
	s_and_b64 vcc, exec, s[88:89]
	s_cbranch_vccnz .LBB0_1091
	s_lshl_b64 s[8:9], s[6:7], 12
	s_add_u32 s8, s22, s8
	s_addc_u32 s9, s1, s9
	v_lshl_add_u64 v[84:85], v[164:165], 1, s[8:9]
	global_load_dwordx2 v[86:87], v[84:85], off nt
	global_load_dwordx2 v[106:107], v[84:85], off offset:512 nt
	global_load_dwordx2 v[110:111], v[84:85], off offset:1024 nt
	global_load_dwordx2 v[114:115], v[84:85], off offset:1536 nt
	global_load_dwordx2 v[146:147], v[84:85], off offset:2048 nt
	global_load_dwordx2 v[154:155], v[84:85], off offset:2560 nt
	global_load_dwordx2 v[158:159], v[84:85], off offset:3072 nt
	global_load_dwordx2 v[162:163], v[84:85], off offset:3584 nt
	s_waitcnt vmcnt(7)
	v_lshlrev_b32_e32 v84, 16, v86
	v_and_b32_e32 v85, 0xffff0000, v86
	v_lshlrev_b32_e32 v86, 16, v87
	v_and_b32_e32 v87, 0xffff0000, v87
	s_waitcnt vmcnt(6)
	v_lshlrev_b32_e32 v104, 16, v106
	v_and_b32_e32 v105, 0xffff0000, v106
	v_lshlrev_b32_e32 v106, 16, v107
	v_and_b32_e32 v107, 0xffff0000, v107
	s_waitcnt vmcnt(5)
	v_lshlrev_b32_e32 v108, 16, v110
	v_and_b32_e32 v109, 0xffff0000, v110
	v_lshlrev_b32_e32 v110, 16, v111
	v_and_b32_e32 v111, 0xffff0000, v111
	s_waitcnt vmcnt(4)
	v_lshlrev_b32_e32 v112, 16, v114
	v_and_b32_e32 v113, 0xffff0000, v114
	v_lshlrev_b32_e32 v114, 16, v115
	v_and_b32_e32 v115, 0xffff0000, v115
	s_waitcnt vmcnt(3)
	v_lshlrev_b32_e32 v144, 16, v146
	v_and_b32_e32 v145, 0xffff0000, v146
	v_lshlrev_b32_e32 v146, 16, v147
	v_and_b32_e32 v147, 0xffff0000, v147
	s_waitcnt vmcnt(2)
	v_lshlrev_b32_e32 v152, 16, v154
	v_and_b32_e32 v153, 0xffff0000, v154
	v_lshlrev_b32_e32 v154, 16, v155
	v_and_b32_e32 v155, 0xffff0000, v155
	s_waitcnt vmcnt(1)
	v_lshlrev_b32_e32 v156, 16, v158
	v_and_b32_e32 v157, 0xffff0000, v158
	v_lshlrev_b32_e32 v158, 16, v159
	v_and_b32_e32 v159, 0xffff0000, v159
	s_waitcnt vmcnt(0)
	v_lshlrev_b32_e32 v160, 16, v162
	v_and_b32_e32 v161, 0xffff0000, v162
	v_lshlrev_b32_e32 v162, 16, v163
	v_and_b32_e32 v163, 0xffff0000, v163
	s_cbranch_execnz .LBB0_1088

; #define GAS __attribute__((address_space(1)))
; DI void phase_norm(const Frame& F0, int nrows, const void* xlat, const void* xctx, int xin_bf16, const bf16* Y, const float* gainY, const float* gate  ,
;                    void* Xout_lat, void* Xout_ctx, int xout_bf16, bf16* Hout, const float* gainH, const float* shift, const float* scale) {
;     ...
;             if (Y) {
; #pragma unroll
;                 for (int j = 0; j < 8; ++j) ybn[j] = *(const GAS v2u*)(Y + (size_t)Rn * DM + j * 256 + co); } }
.LBB0_1088:
	s_lshl_b64 s[4:5], s[4:5], 12
	v_lshl_add_u64 v[190:191], v[166:167], 0, s[4:5]
	global_load_dwordx2 v[176:177], v[190:191], off nt
	global_load_dwordx2 v[178:179], v[190:191], off offset:512 nt
	global_load_dwordx2 v[180:181], v[190:191], off offset:1024 nt
	global_load_dwordx2 v[182:183], v[190:191], off offset:1536 nt
	global_load_dwordx2 v[184:185], v[190:191], off offset:2048 nt
	global_load_dwordx2 v[186:187], v[190:191], off offset:2560 nt
	global_load_dwordx2 v[188:189], v[190:191], off offset:3072 nt
	s_nop 0
	global_load_dwordx2 v[190:191], v[190:191], off offset:3584 nt

; #define GAS __attribute__((address_space(1)))
; DI void norm_load_x(f32x4 (&v)[8], const void* xlat, const void* xctx, int xin_bf16, int R, int co) {
;     if (xin_bf16) { const bf16* xr = R < NLAT ? (const bf16*)xlat + (size_t)R * DM : (const bf16*)xctx + (size_t)(R - NLAT) * DM;
;         v2u t[8];
; #pragma unroll
;         for (int j = 0; j < 8; ++j) t[j] = *(const GAS v2u*)(xr + j * 256 + co);
; #pragma unroll
;         for (int j = 0; j < 8; ++j) v[j] = (f32x4){bflo(t[j].x), bfhi(t[j].x), bflo(t[j].y), bfhi(t[j].y)}; }
;     else { const float* xr = R < NLAT ? (const float*)xlat + (size_t)R * DM : (const float*)xctx + (size_t)(R - NLAT) * DM;
; #pragma unroll
;         for (int j = 0; j < 8; ++j) v[j] = *(const GAS f32x4*)(xr + j * 256 + co); }
; DI void phase_norm(const Frame& F0, int nrows, const void* xlat, const void* xctx, int xin_bf16, const bf16* Y, const float* gainY, const float* gate  ,
;                    void* Xout_lat, void* Xout_ctx, int xout_bf16, bf16* Hout, const float* gainH, const float* shift, const float* scale) {
;     ...
;     if (nit > 0) { const int R0 = NORM_ROW(0); norm_load_x(v, xlat, xctx, xin_bf16, R0, co);
;         if (Y) {
; #pragma unroll
;             for (int j = 0; j < 8; ++j) yb[j] = *(const GAS v2u*)(Y + (size_t)R0 * DM + j * 256 + co); } }
;     f32x4 gt[8], sh[8], sc[8]; int mbp = -1;
.LBB0_1352:
	s_add_u32 s14, s0, 0x15de4000
	s_addc_u32 s15, s1, 0
	s_add_u32 s6, s6, 0x17de4000
	s_addc_u32 s7, s7, 0
	s_add_u32 s0, s8, 0x2de84000
	s_addc_u32 s1, s9, 0
	s_ashr_i32 s5, s4, 31
	v_lshlrev_b32_e32 v68, 2, v2
	s_lshl_b64 s[8:9], s[4:5], 12
	s_add_u32 s8, s0, s8
	v_ashrrev_i32_e32 v69, 31, v68
	s_addc_u32 s9, s1, s9
	v_lshlrev_b64 v[4:5], 1, v[68:69]
	v_lshl_add_u64 v[6:7], s[8:9], 0, v[4:5]
	s_add_i32 s8, s4, 0xffffe000
	s_cmpk_lt_i32 s4, 0x2000
	s_cselect_b32 s5, s5, 0
	s_cselect_b32 s4, s4, s8
	s_cselect_b32 s9, s15, s7
	s_cselect_b32 s16, s14, s6
	s_lshl_b64 s[4:5], s[4:5], 12
	s_add_u32 s4, s16, s4
	s_addc_u32 s5, s9, s5
	global_load_dwordx2 v[74:75], v[6:7], off offset:3584 nt
	global_load_dwordx2 v[76:77], v[6:7], off offset:3072 nt
	global_load_dwordx2 v[78:79], v[6:7], off offset:2560 nt
	global_load_dwordx2 v[80:81], v[6:7], off offset:2048 nt
	global_load_dwordx2 v[86:87], v[6:7], off offset:1536 nt
	global_load_dwordx2 v[100:101], v[6:7], off offset:1024 nt
	global_load_dwordx2 v[116:117], v[6:7], off offset:512 nt
	global_load_dwordx2 v[120:121], v[6:7], off nt
	v_lshl_add_u64 v[6:7], s[4:5], 0, v[4:5]
	global_load_dwordx2 v[8:9], v[6:7], off offset:3584 nt
	v_and_b32_e32 v2, 64, v224
	v_add_u32_e32 v2, 64, v2
	v_readlane_b32 s4, v254, 58
	v_lshl_add_u64 v[70:71], s[0:1], 0, v[4:5]
	v_readlane_b32 s16, v252, 0
	s_ashr_i32 s0, s13, 31
	v_readlane_b32 s1, v254, 48
	s_add_i32 s4, s10, s4
	v_lshlrev_b64 v[4:5], 2, v[68:69]
	v_readlane_b32 s18, v252, 2
	v_readlane_b32 s19, v252, 3
	s_xor_b32 s0, s0, s1
	s_abs_i32 s1, s13
	v_readlane_b32 s10, v254, 28
	v_lshl_add_u64 v[122:123], s[18:19], 0, v[4:5]
	s_mul_hi_u32 s10, s1, s10
	v_readlane_b32 s18, v254, 27
	s_mul_i32 s16, s10, s18
	v_readlane_b32 s17, v252, 1
	s_sub_i32 s1, s1, s16
	s_and_b32 s9, s13, 0x3ff
	s_add_i32 s16, s10, 1
	s_sub_i32 s17, s1, s18
	s_cmp_ge_u32 s1, s18
	s_cselect_b32 s10, s16, s10
	s_cselect_b32 s1, s17, s1
	s_add_i32 s16, s10, 1
	s_cmp_ge_u32 s1, s18
	s_cselect_b32 s1, s16, s10
	s_xor_b32 s1, s1, s0
	s_lshl_b32 s1, s1, 12
	v_lshl_add_u64 v[72:73], s[38:39], 0, v[4:5]
	s_or_b32 s1, s1, s9
	s_lshl_b32 s0, s0, 12
	v_mov_b32_e32 v4, v3
	v_mov_b32_e32 v5, v3
	v_mov_b32_e32 v10, v3
	v_mov_b32_e32 v11, v3
	v_mov_b32_e32 v12, v3
	v_mov_b32_e32 v13, v3
	v_mov_b32_e32 v14, v3
	v_mov_b32_e32 v15, v3
	v_mov_b32_e32 v16, v3
	v_mov_b32_e32 v17, v3
	v_mov_b32_e32 v18, v3
	v_mov_b32_e32 v19, v3
	v_mov_b32_e32 v20, v3
	v_mov_b32_e32 v21, v3
	v_mov_b32_e32 v22, v3
	v_mov_b32_e32 v23, v3
	v_mov_b32_e32 v24, v3
	v_mov_b32_e32 v25, v3
	v_mov_b32_e32 v26, v3
	v_mov_b32_e32 v27, v3
	v_mov_b32_e32 v28, v3
	v_mov_b32_e32 v29, v3
	v_mov_b32_e32 v30, v3
	v_mov_b32_e32 v31, v3
	v_mov_b32_e32 v32, v3
	v_mov_b32_e32 v33, v3
	s_sub_i32 s9, s1, s0
	s_bitset1_b32 s1, 10
	s_mov_b32 s5, 0
	s_mov_b32 s8, -1
	s_sub_i32 s16, s1, s0
	s_waitcnt vmcnt(0)
	v_lshlrev_b32_e32 v82, 16, v8
	v_and_b32_e32 v83, 0xffff0000, v8
	v_lshlrev_b32_e32 v84, 16, v9
	v_and_b32_e32 v85, 0xffff0000, v9
	global_load_dwordx2 v[8:9], v[6:7], off offset:3072 nt
	s_waitcnt vmcnt(0)
	v_lshlrev_b32_e32 v88, 16, v8
	v_and_b32_e32 v89, 0xffff0000, v8
	v_lshlrev_b32_e32 v94, 16, v9
	v_and_b32_e32 v95, 0xffff0000, v9
	global_load_dwordx2 v[8:9], v[6:7], off offset:2560 nt
	s_waitcnt vmcnt(0)
	v_lshlrev_b32_e32 v90, 16, v8
	v_and_b32_e32 v91, 0xffff0000, v8
	v_lshlrev_b32_e32 v98, 16, v9
	v_and_b32_e32 v99, 0xffff0000, v9
	global_load_dwordx2 v[8:9], v[6:7], off offset:2048 nt
	s_waitcnt vmcnt(0)
	v_lshlrev_b32_e32 v92, 16, v8
	v_and_b32_e32 v93, 0xffff0000, v8
	v_lshlrev_b32_e32 v104, 16, v9
	v_and_b32_e32 v105, 0xffff0000, v9
	global_load_dwordx2 v[8:9], v[6:7], off offset:1536 nt
	s_waitcnt vmcnt(0)
	v_lshlrev_b32_e32 v96, 16, v8
	v_and_b32_e32 v97, 0xffff0000, v8
	v_lshlrev_b32_e32 v108, 16, v9
	v_and_b32_e32 v109, 0xffff0000, v9
	global_load_dwordx2 v[8:9], v[6:7], off offset:1024 nt
	s_waitcnt vmcnt(0)
	v_lshlrev_b32_e32 v102, 16, v8
	v_and_b32_e32 v103, 0xffff0000, v8
	v_lshlrev_b32_e32 v112, 16, v9
	v_and_b32_e32 v113, 0xffff0000, v9
	global_load_dwordx2 v[8:9], v[6:7], off offset:512 nt
	s_waitcnt vmcnt(0)
	v_lshlrev_b32_e32 v106, 16, v8
	global_load_dwordx2 v[6:7], v[6:7], off nt
	v_and_b32_e32 v107, 0xffff0000, v8
	v_lshlrev_b32_e32 v114, 16, v9
	v_and_b32_e32 v115, 0xffff0000, v9
	v_mov_b32_e32 v8, v3
	v_mov_b32_e32 v9, v3
	s_waitcnt vmcnt(0)
	v_lshlrev_b32_e32 v110, 16, v6
	v_and_b32_e32 v111, 0xffff0000, v6
	v_xor_b32_e32 v6, 1, v224
	v_cmp_lt_i32_e32 vcc, v6, v2
	v_lshlrev_b32_e32 v118, 16, v7
	v_and_b32_e32 v119, 0xffff0000, v7
	v_cndmask_b32_e32 v6, v224, v6, vcc
	v_lshlrev_b32_e32 v156, 2, v6
	v_xor_b32_e32 v6, 2, v224
	v_cmp_lt_i32_e32 vcc, v6, v2
	v_mov_b32_e32 v7, v3
	s_nop 0
	v_cndmask_b32_e32 v6, v224, v6, vcc
	v_lshlrev_b32_e32 v157, 2, v6
	v_xor_b32_e32 v6, 4, v224
	v_cmp_lt_i32_e32 vcc, v6, v2
	s_nop 1
	v_cndmask_b32_e32 v6, v224, v6, vcc
	v_lshlrev_b32_e32 v158, 2, v6
	v_xor_b32_e32 v6, 8, v224
	v_cmp_lt_i32_e32 vcc, v6, v2
	s_nop 1
	v_cndmask_b32_e32 v6, v224, v6, vcc
	v_lshlrev_b32_e32 v159, 2, v6
	v_xor_b32_e32 v6, 16, v224
	v_cmp_lt_i32_e32 vcc, v6, v2
	s_nop 1
	v_cndmask_b32_e32 v6, v224, v6, vcc
	v_lshlrev_b32_e32 v160, 2, v6
	v_xor_b32_e32 v6, 32, v224
	v_cmp_lt_i32_e32 vcc, v6, v2
	s_nop 1
	v_cndmask_b32_e32 v2, v224, v6, vcc
	v_mov_b32_e32 v6, v3
	v_lshlrev_b32_e32 v161, 2, v2
	v_mov_b32_e32 v2, v3
	v_mov_b64_e32 v[34:35], v[32:33]
	v_mov_b64_e32 v[32:33], v[30:31]
	v_mov_b64_e32 v[30:31], v[28:29]
	v_mov_b64_e32 v[28:29], v[26:27]
	v_mov_b64_e32 v[26:27], v[24:25]
	v_mov_b64_e32 v[24:25], v[22:23]
	v_mov_b64_e32 v[22:23], v[20:21]
	v_mov_b64_e32 v[20:21], v[18:19]
	v_mov_b64_e32 v[18:19], v[16:17]
	v_mov_b64_e32 v[16:17], v[14:15]
	v_mov_b64_e32 v[14:15], v[12:13]
	v_mov_b64_e32 v[12:13], v[10:11]
	v_mov_b64_e32 v[10:11], v[8:9]
	v_mov_b64_e32 v[8:9], v[6:7]
	v_mov_b64_e32 v[6:7], v[4:5]
	v_mov_b64_e32 v[4:5], v[2:3]
	s_branch .LBB0_1354

; #define GAS __attribute__((address_space(1)))
; DI void phase_norm(const Frame& F0, int nrows, const void* xlat, const void* xctx, int xin_bf16, const bf16* Y, const float* gainY, const float* gate  ,
;                    void* Xout_lat, void* Xout_ctx, int xout_bf16, bf16* Hout, const float* gainH, const float* shift, const float* scale) {
;     ...
;         const int R = NORM_ROW(it); const int mb = row_mb(R), Rn = NORM_ROW(it + 1);
;         f32x4 vn[8]; v2u ybn[8];
;         if (it + 1 < nit) { norm_load_x(vn, xlat, xctx, xin_bf16, Rn, co);
;             if (Y) {
; #pragma unroll
;                 for (int j = 0; j < 8; ++j) ybn[j] = *(const GAS v2u*)(Y + (size_t)Rn * DM + j * 256 + co); } }
.LBB0_1360:
	s_cmp_ge_i32 s5, s12
	s_cbranch_scc1 .LBB0_1362
	s_add_i32 s10, s0, 0xffffe000
	s_ashr_i32 s1, s0, 31
	s_cmpk_lt_i32 s0, 0x2000
	s_cselect_b32 s19, s1, 0
	s_cselect_b32 s18, s0, s10
	s_cselect_b32 s10, s15, s7
	s_cselect_b32 s22, s14, s6
	s_lshl_b64 s[18:19], s[18:19], 12
	s_add_u32 s18, s22, s18
	s_addc_u32 s19, s10, s19
	s_lshl_b64 s[0:1], s[0:1], 12
	v_lshl_add_u64 v[4:5], v[68:69], 1, s[18:19]
	v_lshl_add_u64 v[124:125], v[70:71], 0, s[0:1]
	global_load_dwordx2 v[6:7], v[4:5], off nt
	global_load_dwordx2 v[10:11], v[4:5], off offset:512 nt
	global_load_dwordx2 v[14:15], v[4:5], off offset:1024 nt
	global_load_dwordx2 v[18:19], v[4:5], off offset:1536 nt
	global_load_dwordx2 v[22:23], v[4:5], off offset:2048 nt
	global_load_dwordx2 v[26:27], v[4:5], off offset:2560 nt
	global_load_dwordx2 v[30:31], v[4:5], off offset:3072 nt
	global_load_dwordx2 v[34:35], v[4:5], off offset:3584 nt
	global_load_dwordx2 v[138:139], v[124:125], off nt
	global_load_dwordx2 v[136:137], v[124:125], off offset:512 nt
	global_load_dwordx2 v[134:135], v[124:125], off offset:1024 nt
	global_load_dwordx2 v[132:133], v[124:125], off offset:1536 nt
	global_load_dwordx2 v[130:131], v[124:125], off offset:2048 nt
	global_load_dwordx2 v[128:129], v[124:125], off offset:2560 nt
	global_load_dwordx2 v[126:127], v[124:125], off offset:3072 nt
	s_nop 0
	global_load_dwordx2 v[124:125], v[124:125], off offset:3584 nt
	s_waitcnt vmcnt(15)
	v_lshlrev_b32_e32 v4, 16, v6
	v_and_b32_e32 v5, 0xffff0000, v6
	v_lshlrev_b32_e32 v6, 16, v7
	v_and_b32_e32 v7, 0xffff0000, v7
	s_waitcnt vmcnt(14)
	v_lshlrev_b32_e32 v8, 16, v10
	v_and_b32_e32 v9, 0xffff0000, v10
	v_lshlrev_b32_e32 v10, 16, v11
	v_and_b32_e32 v11, 0xffff0000, v11
	s_waitcnt vmcnt(13)
	v_lshlrev_b32_e32 v12, 16, v14
	v_and_b32_e32 v13, 0xffff0000, v14
	v_lshlrev_b32_e32 v14, 16, v15
	v_and_b32_e32 v15, 0xffff0000, v15
	s_waitcnt vmcnt(12)
	v_lshlrev_b32_e32 v16, 16, v18
	v_and_b32_e32 v17, 0xffff0000, v18
	v_lshlrev_b32_e32 v18, 16, v19
	v_and_b32_e32 v19, 0xffff0000, v19
	s_waitcnt vmcnt(11)
	v_lshlrev_b32_e32 v20, 16, v22
	v_and_b32_e32 v21, 0xffff0000, v22
	v_lshlrev_b32_e32 v22, 16, v23
	v_and_b32_e32 v23, 0xffff0000, v23
	s_waitcnt vmcnt(10)
	v_lshlrev_b32_e32 v24, 16, v26
	v_and_b32_e32 v25, 0xffff0000, v26
	v_lshlrev_b32_e32 v26, 16, v27
	v_and_b32_e32 v27, 0xffff0000, v27
	s_waitcnt vmcnt(9)
	v_lshlrev_b32_e32 v28, 16, v30
	v_and_b32_e32 v29, 0xffff0000, v30
	v_lshlrev_b32_e32 v30, 16, v31
	v_and_b32_e32 v31, 0xffff0000, v31
	s_waitcnt vmcnt(8)
	v_lshlrev_b32_e32 v32, 16, v34
	v_and_b32_e32 v33, 0xffff0000, v34
	v_lshlrev_b32_e32 v34, 16, v35
	v_and_b32_e32 v35, 0xffff0000, v35

; #define GAS __attribute__((address_space(1)))
; DI void phase_norm(const Frame& F0, int nrows, const void* xlat, const void* xctx, int xin_bf16, const bf16* Y, const float* gainY, const float* gate  ,
;                    void* Xout_lat, void* Xout_ctx, int xout_bf16, bf16* Hout, const float* gainH, const float* shift, const float* scale) {
;     ...
;     if (nit > 0) { const int R0 = NORM_ROW(0); norm_load_x(v, xlat, xctx, xin_bf16, R0, co);
;         if (Y) {
; #pragma unroll
;             for (int j = 0; j < 8; ++j) yb[j] = *(const GAS v2u*)(Y + (size_t)R0 * DM + j * 256 + co); } }
;     f32x4 gt[8], sh[8], sc[8]; int mbp = -1;
;     for (int it = 0; it < nit; ++it) {
;         const int R = NORM_ROW(it); const int mb = row_mb(R), Rn = NORM_ROW(it + 1);
;         f32x4 vn[8]; v2u ybn[8];
;         if (it + 1 < nit) { norm_load_x(vn, xlat, xctx, xin_bf16, Rn, co);
;             if (Y) {
; #pragma unroll
;                 for (int j = 0; j < 8; ++j) ybn[j] = *(const GAS v2u*)(Y + (size_t)Rn * DM + j * 256 + co); } }
;         if (mb != mbp) { mbp = mb;
;             if (Y) {
; #pragma unroll
;                 for (int j = 0; j < 8; ++j) gt[j] = *(const GAS f32x4*)(gate + (size_t)mb * NADA + j * 256 + co); }
;             if (Hout) {
; #pragma unroll
;                 for (int j = 0; j < 8; ++j) { sh[j] = *(const GAS f32x4*)(shift + (size_t)mb * NADA + j * 256 + co); sc[j] = *(const GAS f32x4*)(scale + (size_t)mb * NADA + j * 256 + co); } } }
.LBB0_1374:
	s_add_u32 s4, s4, s65
	s_addc_u32 s5, s5, 0
	s_add_u32 s12, s6, 0x15de4000
	s_addc_u32 s13, s7, 0
	s_add_u32 s16, s42, 0x17de4000
	s_addc_u32 s17, s43, 0
	s_add_u32 s6, s44, 0x2de84000
	s_addc_u32 s7, s45, 0
	s_add_u32 s18, s34, 0x15de4000
	s_addc_u32 s19, s35, 0
	s_add_u32 s24, s36, 0x17de4000
	s_addc_u32 s25, s37, 0
	s_ashr_i32 s9, s8, 31
	v_lshlrev_b32_e32 v132, 2, v2
	s_lshl_b64 s[22:23], s[8:9], 12
	s_add_u32 s22, s6, s22
	v_ashrrev_i32_e32 v133, 31, v132
	s_addc_u32 s23, s7, s23
	v_lshlrev_b64 v[4:5], 1, v[132:133]
	v_lshl_add_u64 v[6:7], s[22:23], 0, v[4:5]
	s_add_i32 s22, s8, 0xffffe000
	s_cmpk_lt_i32 s8, 0x2000
	s_cselect_b32 s9, s9, 0
	s_cselect_b32 s8, s8, s22
	s_cselect_b32 s23, s13, s17
	s_cselect_b32 s27, s12, s16
	s_lshl_b64 s[8:9], s[8:9], 12
	s_add_u32 s8, s27, s8
	s_addc_u32 s9, s23, s9
	global_load_dwordx2 v[152:153], v[6:7], off offset:3584 nt
	global_load_dwordx2 v[156:157], v[6:7], off offset:3072 nt
	global_load_dwordx2 v[160:161], v[6:7], off offset:2560 nt
	s_waitcnt lgkmcnt(0)
	global_load_dwordx2 v[162:163], v[6:7], off offset:2048 nt
	global_load_dwordx2 v[168:169], v[6:7], off offset:1536 nt
	global_load_dwordx2 v[172:173], v[6:7], off offset:1024 nt
	global_load_dwordx2 v[176:177], v[6:7], off offset:512 nt
	global_load_dwordx2 v[178:179], v[6:7], off nt
	v_lshl_add_u64 v[6:7], s[8:9], 0, v[4:5]
	global_load_dwordx2 v[8:9], v[6:7], off offset:3584 nt
	v_lshl_add_u64 v[134:135], s[6:7], 0, v[4:5]
	v_lshl_add_u64 v[4:5], s[0:1], 0, v[4:5]
	s_mov_b64 s[0:1], 0x1a1e4000
	v_and_b32_e32 v2, 64, v224
	v_lshl_add_u64 v[142:143], v[4:5], 0, s[0:1]
	v_add_u32_e32 v2, 64, v2
	v_xor_b32_e32 v4, 1, v224
	v_cmp_lt_i32_e32 vcc, v4, v2
	s_ashr_i32 s0, s15, 31
	v_readlane_b32 s1, v254, 48
	v_cndmask_b32_e32 v4, v224, v4, vcc
	v_lshlrev_b32_e32 v208, 2, v4
	v_xor_b32_e32 v4, 2, v224
	v_cmp_lt_i32_e32 vcc, v4, v2
	s_xor_b32 s0, s0, s1
	s_abs_i32 s1, s15
	v_cndmask_b32_e32 v4, v224, v4, vcc
	v_lshlrev_b32_e32 v209, 2, v4
	v_xor_b32_e32 v4, 4, v224
	v_readlane_b32 s22, v254, 27
	v_cmp_lt_i32_e32 vcc, v4, v2
	s_add_i32 s8, s10, s21
	s_and_b32 s9, s15, 0x3ff
	v_cndmask_b32_e32 v4, v224, v4, vcc
	v_lshlrev_b32_e32 v210, 2, v4
	v_xor_b32_e32 v4, 8, v224
	v_cmp_lt_i32_e32 vcc, v4, v2
	v_mov_b32_e32 v5, v3
	v_mov_b32_e32 v10, v3
	v_cndmask_b32_e32 v4, v224, v4, vcc
	v_lshlrev_b32_e32 v211, 2, v4
	v_xor_b32_e32 v4, 16, v224
	v_cmp_lt_i32_e32 vcc, v4, v2
	v_mov_b32_e32 v11, v3
	v_mov_b32_e32 v12, v3
	v_cndmask_b32_e32 v4, v224, v4, vcc
	v_lshlrev_b32_e32 v212, 2, v4
	v_xor_b32_e32 v4, 32, v224
	v_cmp_lt_i32_e32 vcc, v4, v2
	v_mov_b32_e32 v13, v3
	v_mov_b32_e32 v14, v3
	v_cndmask_b32_e32 v2, v224, v4, vcc
	v_mov_b32_e32 v4, v3
	v_mov_b32_e32 v15, v3
	v_mov_b32_e32 v16, v3
	v_mov_b32_e32 v17, v3
	v_mov_b32_e32 v18, v3
	v_mov_b32_e32 v19, v3
	v_mov_b32_e32 v20, v3
	v_mov_b32_e32 v21, v3
	v_mov_b32_e32 v22, v3
	v_mov_b32_e32 v23, v3
	v_mov_b32_e32 v24, v3
	v_mov_b32_e32 v25, v3
	v_mov_b32_e32 v26, v3
	v_mov_b32_e32 v27, v3
	v_mov_b32_e32 v28, v3
	v_mov_b32_e32 v29, v3
	v_mov_b32_e32 v30, v3
	v_mov_b32_e32 v31, v3
	v_mov_b32_e32 v32, v3
	v_mov_b32_e32 v33, v3
	v_lshlrev_b32_e32 v213, 2, v2
	v_mov_b32_e32 v2, v3
	s_mov_b32 s6, 0
	s_mov_b32 s7, -1
	s_waitcnt vmcnt(0)
	v_lshlrev_b32_e32 v144, 16, v8
	v_and_b32_e32 v145, 0xffff0000, v8
	v_lshlrev_b32_e32 v146, 16, v9
	v_and_b32_e32 v147, 0xffff0000, v9
	global_load_dwordx2 v[8:9], v[6:7], off offset:3072 nt
	s_waitcnt vmcnt(0)
	v_lshlrev_b32_e32 v148, 16, v8
	v_and_b32_e32 v149, 0xffff0000, v8
	v_lshlrev_b32_e32 v150, 16, v9
	v_and_b32_e32 v151, 0xffff0000, v9
	global_load_dwordx2 v[8:9], v[6:7], off offset:2560 nt
	s_waitcnt vmcnt(0)
	v_lshlrev_b32_e32 v154, 16, v8
	v_and_b32_e32 v155, 0xffff0000, v8
	v_lshlrev_b32_e32 v158, 16, v9
	v_and_b32_e32 v159, 0xffff0000, v9
	global_load_dwordx2 v[8:9], v[6:7], off offset:2048 nt
	s_waitcnt vmcnt(0)
	v_lshlrev_b32_e32 v164, 16, v8
	v_and_b32_e32 v165, 0xffff0000, v8
	v_lshlrev_b32_e32 v166, 16, v9
	v_and_b32_e32 v167, 0xffff0000, v9
	global_load_dwordx2 v[8:9], v[6:7], off offset:1536 nt
	s_waitcnt vmcnt(0)
	v_lshlrev_b32_e32 v170, 16, v8
	v_and_b32_e32 v171, 0xffff0000, v8
	v_lshlrev_b32_e32 v174, 16, v9
	v_and_b32_e32 v175, 0xffff0000, v9
	global_load_dwordx2 v[8:9], v[6:7], off offset:1024 nt
	s_waitcnt vmcnt(0)
	v_lshlrev_b32_e32 v180, 16, v8
	v_and_b32_e32 v181, 0xffff0000, v8
	v_lshlrev_b32_e32 v182, 16, v9
	v_and_b32_e32 v183, 0xffff0000, v9
	global_load_dwordx2 v[8:9], v[6:7], off offset:512 nt
	s_waitcnt vmcnt(0)
	v_lshlrev_b32_e32 v184, 16, v8
	global_load_dwordx2 v[6:7], v[6:7], off nt
	v_and_b32_e32 v185, 0xffff0000, v8
	v_lshlrev_b32_e32 v186, 16, v9
	v_and_b32_e32 v187, 0xffff0000, v9
	v_mov_b32_e32 v8, v3
	v_mov_b32_e32 v9, v3
	s_waitcnt vmcnt(0)
	v_lshlrev_b32_e32 v188, 16, v6
	v_and_b32_e32 v189, 0xffff0000, v6
	v_lshlrev_b32_e32 v190, 16, v7
	v_and_b32_e32 v191, 0xffff0000, v7
	v_lshlrev_b64 v[6:7], 2, v[132:133]
	v_lshl_add_u64 v[136:137], s[38:39], 0, v[6:7]
	v_lshl_add_u64 v[6:7], s[4:5], 0, v[6:7]
	s_mov_b64 s[4:5], 0x34000
	v_lshl_add_u64 v[138:139], v[6:7], 0, s[4:5]
	s_mov_b64 s[4:5], 0x36000
	v_lshl_add_u64 v[140:141], v[6:7], 0, s[4:5]
	v_readlane_b32 s4, v254, 28
	s_mul_hi_u32 s4, s1, s4
	s_mul_i32 s5, s4, s22
	s_sub_i32 s1, s1, s5
	s_add_i32 s5, s4, 1
	s_sub_i32 s10, s1, s22
	s_cmp_ge_u32 s1, s22
	s_cselect_b32 s4, s5, s4
	s_cselect_b32 s1, s10, s1
	s_add_i32 s5, s4, 1
	s_cmp_ge_u32 s1, s22
	s_cselect_b32 s1, s5, s4
	s_xor_b32 s1, s1, s0
	s_lshl_b32 s1, s1, 12
	s_or_b32 s1, s1, s9
	s_lshl_b32 s0, s0, 12
	v_mov_b32_e32 v6, v3
	v_mov_b32_e32 v7, v3
	s_sub_i32 s9, s1, s0
	s_bitset1_b32 s1, 10
	v_mov_b64_e32 v[34:35], v[32:33]
	s_sub_i32 s28, s1, s0
	v_mov_b64_e32 v[32:33], v[30:31]
	v_mov_b64_e32 v[30:31], v[28:29]
	v_mov_b64_e32 v[28:29], v[26:27]
	v_mov_b64_e32 v[26:27], v[24:25]
	v_mov_b64_e32 v[24:25], v[22:23]
	v_mov_b64_e32 v[22:23], v[20:21]
	v_mov_b64_e32 v[20:21], v[18:19]
	v_mov_b64_e32 v[18:19], v[16:17]
	v_mov_b64_e32 v[16:17], v[14:15]
	v_mov_b64_e32 v[14:15], v[12:13]
	v_mov_b64_e32 v[12:13], v[10:11]
	v_mov_b64_e32 v[10:11], v[8:9]
	v_mov_b64_e32 v[8:9], v[6:7]
	v_mov_b64_e32 v[6:7], v[4:5]
	v_mov_b64_e32 v[4:5], v[2:3]
	s_branch .LBB0_1376

; #define GAS __attribute__((address_space(1)))
; DI void phase_norm(const Frame& F0, int nrows, const void* xlat, const void* xctx, int xin_bf16, const bf16* Y, const float* gainY, const float* gate  ,
;                    void* Xout_lat, void* Xout_ctx, int xout_bf16, bf16* Hout, const float* gainH, const float* shift, const float* scale) {
;     ...
;         const int R = NORM_ROW(it); const int mb = row_mb(R), Rn = NORM_ROW(it + 1);
;         f32x4 vn[8]; v2u ybn[8];
;         if (it + 1 < nit) { norm_load_x(vn, xlat, xctx, xin_bf16, Rn, co);
;             if (Y) {
; #pragma unroll
;                 for (int j = 0; j < 8; ++j) ybn[j] = *(const GAS v2u*)(Y + (size_t)Rn * DM + j * 256 + co); } }
.LBB0_1382:
	s_cmp_ge_i32 s6, s14
	s_cbranch_scc1 .LBB0_1384
	s_add_i32 s1, s4, 0xffffe000
	s_ashr_i32 s5, s4, 31
	s_cmpk_lt_i32 s4, 0x2000
	s_cselect_b32 s23, s5, 0
	s_cselect_b32 s22, s4, s1
	s_cselect_b32 s1, s13, s17
	s_cselect_b32 s10, s12, s16
	s_lshl_b64 s[22:23], s[22:23], 12
	s_add_u32 s22, s10, s22
	s_addc_u32 s23, s1, s23
	s_lshl_b64 s[4:5], s[4:5], 12
	v_lshl_add_u64 v[4:5], v[132:133], 1, s[22:23]
	v_lshl_add_u64 v[192:193], v[134:135], 0, s[4:5]
	global_load_dwordx2 v[6:7], v[4:5], off nt
	global_load_dwordx2 v[10:11], v[4:5], off offset:512 nt
	global_load_dwordx2 v[14:15], v[4:5], off offset:1024 nt
	global_load_dwordx2 v[18:19], v[4:5], off offset:1536 nt
	global_load_dwordx2 v[22:23], v[4:5], off offset:2048 nt
	global_load_dwordx2 v[26:27], v[4:5], off offset:2560 nt
	global_load_dwordx2 v[30:31], v[4:5], off offset:3072 nt
	global_load_dwordx2 v[34:35], v[4:5], off offset:3584 nt
	global_load_dwordx2 v[206:207], v[192:193], off nt
	global_load_dwordx2 v[204:205], v[192:193], off offset:512 nt
	global_load_dwordx2 v[202:203], v[192:193], off offset:1024 nt
	global_load_dwordx2 v[200:201], v[192:193], off offset:1536 nt
	global_load_dwordx2 v[198:199], v[192:193], off offset:2048 nt
	global_load_dwordx2 v[196:197], v[192:193], off offset:2560 nt
	global_load_dwordx2 v[194:195], v[192:193], off offset:3072 nt
	s_nop 0
	global_load_dwordx2 v[192:193], v[192:193], off offset:3584 nt
	s_waitcnt vmcnt(15)
	v_lshlrev_b32_e32 v4, 16, v6
	v_and_b32_e32 v5, 0xffff0000, v6
	v_lshlrev_b32_e32 v6, 16, v7
	v_and_b32_e32 v7, 0xffff0000, v7
	s_waitcnt vmcnt(14)
	v_lshlrev_b32_e32 v8, 16, v10
	v_and_b32_e32 v9, 0xffff0000, v10
	v_lshlrev_b32_e32 v10, 16, v11
	v_and_b32_e32 v11, 0xffff0000, v11
	s_waitcnt vmcnt(13)
	v_lshlrev_b32_e32 v12, 16, v14
	v_and_b32_e32 v13, 0xffff0000, v14
	v_lshlrev_b32_e32 v14, 16, v15
	v_and_b32_e32 v15, 0xffff0000, v15
	s_waitcnt vmcnt(12)
	v_lshlrev_b32_e32 v16, 16, v18
	v_and_b32_e32 v17, 0xffff0000, v18
	v_lshlrev_b32_e32 v18, 16, v19
	v_and_b32_e32 v19, 0xffff0000, v19
	s_waitcnt vmcnt(11)
	v_lshlrev_b32_e32 v20, 16, v22
	v_and_b32_e32 v21, 0xffff0000, v22
	v_lshlrev_b32_e32 v22, 16, v23
	v_and_b32_e32 v23, 0xffff0000, v23
	s_waitcnt vmcnt(10)
	v_lshlrev_b32_e32 v24, 16, v26
	v_and_b32_e32 v25, 0xffff0000, v26
	v_lshlrev_b32_e32 v26, 16, v27
	v_and_b32_e32 v27, 0xffff0000, v27
	s_waitcnt vmcnt(9)
	v_lshlrev_b32_e32 v28, 16, v30
	v_and_b32_e32 v29, 0xffff0000, v30
	v_lshlrev_b32_e32 v30, 16, v31
	v_and_b32_e32 v31, 0xffff0000, v31
	s_waitcnt vmcnt(8)
	v_lshlrev_b32_e32 v32, 16, v34
	v_and_b32_e32 v33, 0xffff0000, v34
	v_lshlrev_b32_e32 v34, 16, v35
	v_and_b32_e32 v35, 0xffff0000, v35
